# P0 rmsnorm: g_pre hoisted, next row loads prefetched
# baseline (speedup 1.0000x reference)
.LBB0_120:
	s_or_b64 exec, exec, s[0:1]
	v_ashrrev_i32_e32 v2, 6, v2
	s_mov_b32 s0, 0x8000
	v_cmp_gt_i32_e32 vcc, s0, v2
	s_and_saveexec_b64 s[0:1], vcc
	s_cbranch_execz .LBB0_123
	v_mbcnt_lo_u32_b32 v1, -1, 0
	v_mbcnt_hi_u32_b32 v3, -1, v1
	v_and_b32_e32 v1, 64, v3
	v_add_u32_e32 v4, 64, v1
	v_xor_b32_e32 v1, 32, v3
	v_cmp_lt_i32_e32 vcc, v1, v4
	v_xor_b32_e32 v5, 16, v3
	v_and_b32_e32 v15, 63, v0
	v_cndmask_b32_e32 v1, v3, v1, vcc
	v_cmp_lt_i32_e32 vcc, v5, v4
	s_ashr_i32 s2, s8, 6
	v_lshlrev_b32_e32 v8, 6, v15
	v_cndmask_b32_e32 v5, v3, v5, vcc
	v_lshlrev_b32_e32 v10, 2, v5
	v_xor_b32_e32 v5, 8, v3
	v_cmp_lt_i32_e32 vcc, v5, v4
	v_mov_b32_e32 v9, 0
	s_mov_b64 s[8:9], 0x1400410
	v_cndmask_b32_e32 v5, v3, v5, vcc
	v_lshlrev_b32_e32 v11, 2, v5
	v_xor_b32_e32 v5, 4, v3
	v_cmp_lt_i32_e32 vcc, v5, v4
	s_ashr_i32 s3, s2, 31
	v_lshlrev_b32_e32 v1, 2, v1
	v_cndmask_b32_e32 v5, v3, v5, vcc
	v_lshlrev_b32_e32 v12, 2, v5
	v_xor_b32_e32 v5, 2, v3
	v_cmp_lt_i32_e32 vcc, v5, v4
	s_lshl_b64 s[10:11], s[2:3], 12
	s_mov_b64 s[12:13], 0
	v_cndmask_b32_e32 v5, v3, v5, vcc
	v_lshlrev_b32_e32 v13, 2, v5
	v_xor_b32_e32 v5, 1, v3
	v_cmp_lt_i32_e32 vcc, v5, v4
	s_movk_i32 s14, 0x7fff
	s_nop 0
	v_cndmask_b32_e32 v3, v3, v5, vcc
	v_lshlrev_b32_e32 v14, 2, v3
	v_ashrrev_i32_e32 v3, 31, v2
	v_lshlrev_b64 v[6:7], 11, v[2:3]
	v_lshl_or_b32 v6, v15, 5, v6
	v_lshlrev_b64 v[16:17], 12, v[2:3]
	v_lshl_add_u64 v[6:7], s[62:63], 0, v[6:7]
	v_or_b32_e32 v16, v16, v8
	v_lshl_add_u64 v[4:5], s[66:67], 0, v[8:9]
	v_lshl_add_u64 v[6:7], v[6:7], 0, s[8:9]
	s_lshl_b64 s[8:9], s[2:3], 11
	v_lshl_add_u64 v[8:9], s[64:65], 0, v[16:17]
	v_mov_b32_e32 v3, 0x358637bd
	s_mov_b32 s3, 0x800000
	global_load_dwordx4 v[32:35], v[4:5], off offset:16
	global_load_dwordx4 v[36:39], v[4:5], off
	global_load_dwordx4 v[40:43], v[4:5], off offset:48
	global_load_dwordx4 v[44:47], v[4:5], off offset:32
	global_load_dwordx4 v[16:19], v[8:9], off
	global_load_dwordx4 v[20:23], v[8:9], off offset:16
	global_load_dwordx4 v[24:27], v[8:9], off offset:32
	global_load_dwordx4 v[28:31], v[8:9], off offset:48
.LBB0_122:
	v_add_u32_e32 v82, s2, v2
	v_cmp_ge_i32_e64 s[16:17], s14, v82
	v_lshl_add_u64 v[80:81], v[8:9], 0, s[10:11]
	s_nop 0
	v_cndmask_b32_e64 v80, v8, v80, s[16:17]
	v_cndmask_b32_e64 v81, v9, v81, s[16:17]
	global_load_dwordx4 v[64:67], v[80:81], off
	global_load_dwordx4 v[68:71], v[80:81], off offset:16
	global_load_dwordx4 v[72:75], v[80:81], off offset:32
	global_load_dwordx4 v[76:79], v[80:81], off offset:48
	v_mov_b32_e32 v2, v82
	v_mov_b32_e32 v8, v80
	v_mov_b32_e32 v9, v81
	s_waitcnt vmcnt(4)
	v_pk_mul_f32 v[48:49], v[16:17], v[16:17]
	v_pk_fma_f32 v[48:49], v[18:19], v[18:19], v[48:49]
	v_pk_fma_f32 v[48:49], v[20:21], v[20:21], v[48:49]
	v_pk_fma_f32 v[48:49], v[22:23], v[22:23], v[48:49]
	v_pk_fma_f32 v[48:49], v[24:25], v[24:25], v[48:49]
	v_pk_fma_f32 v[48:49], v[26:27], v[26:27], v[48:49]
	v_pk_fma_f32 v[48:49], v[28:29], v[28:29], v[48:49]
	v_pk_fma_f32 v[48:49], v[30:31], v[30:31], v[48:49]
	v_add_f32_e32 v15, v48, v49
	ds_bpermute_b32 v48, v1, v15
	s_waitcnt lgkmcnt(0)
	v_add_f32_e32 v15, v15, v48
	ds_bpermute_b32 v48, v10, v15
	s_waitcnt lgkmcnt(0)
	v_add_f32_e32 v15, v15, v48
	ds_bpermute_b32 v48, v11, v15
	s_waitcnt lgkmcnt(0)
	v_add_f32_e32 v15, v15, v48
	ds_bpermute_b32 v48, v12, v15
	s_waitcnt lgkmcnt(0)
	v_add_f32_e32 v15, v15, v48
	ds_bpermute_b32 v48, v13, v15
	s_waitcnt lgkmcnt(0)
	v_add_f32_e32 v15, v15, v48
	ds_bpermute_b32 v48, v14, v15
	s_waitcnt lgkmcnt(0)
	v_add_f32_e32 v15, v15, v48
	v_fmamk_f32 v15, v15, 0x3a800000, v3
	v_mul_f32_e32 v48, 0x4b800000, v15
	v_cmp_gt_f32_e32 vcc, s3, v15
	s_nop 1
	v_cndmask_b32_e32 v15, v15, v48, vcc
	v_rsq_f32_e32 v15, v15
	s_nop 0
	v_mul_f32_e32 v48, 0x45800000, v15
	v_cndmask_b32_e32 v48, v15, v48, vcc
	v_pk_mul_f32 v[16:17], v[16:17], v[48:49] op_sel_hi:[1,0]
	v_pk_mul_f32 v[18:19], v[18:19], v[48:49] op_sel_hi:[1,0]
	v_pk_mul_f32 v[20:21], v[20:21], v[48:49] op_sel_hi:[1,0]
	v_pk_mul_f32 v[22:23], v[22:23], v[48:49] op_sel_hi:[1,0]
	v_pk_mul_f32 v[24:25], v[24:25], v[48:49] op_sel_hi:[1,0]
	v_pk_mul_f32 v[26:27], v[26:27], v[48:49] op_sel_hi:[1,0]
	v_pk_mul_f32 v[28:29], v[28:29], v[48:49] op_sel_hi:[1,0]
	v_pk_mul_f32 v[30:31], v[30:31], v[48:49] op_sel_hi:[1,0]
	v_pk_mul_f32 v[16:17], v[16:17], v[36:37]
	v_pk_mul_f32 v[18:19], v[18:19], v[38:39]
	v_pk_mul_f32 v[20:21], v[20:21], v[32:33]
	v_pk_mul_f32 v[22:23], v[22:23], v[34:35]
	v_pk_mul_f32 v[24:25], v[24:25], v[44:45]
	v_pk_mul_f32 v[26:27], v[26:27], v[46:47]
	v_pk_mul_f32 v[28:29], v[28:29], v[40:41]
	v_pk_mul_f32 v[30:31], v[30:31], v[42:43]
	v_cvt_pk_bf16_f32 v16, v16, v17
	v_cvt_pk_bf16_f32 v17, v18, v19
	v_cvt_pk_bf16_f32 v18, v20, v21
	v_cvt_pk_bf16_f32 v19, v22, v23
	v_cvt_pk_bf16_f32 v20, v24, v25
	v_cvt_pk_bf16_f32 v21, v26, v27
	v_cvt_pk_bf16_f32 v22, v28, v29
	v_cvt_pk_bf16_f32 v23, v30, v31
	global_store_dwordx4 v[6:7], v[16:19], off offset:-16
	global_store_dwordx4 v[6:7], v[20:23], off
	v_lshl_add_u64 v[6:7], v[6:7], 0, s[8:9]
	s_and_b64 vcc, exec, s[16:17]
	s_cbranch_vccz .Lp0_done
	v_add_u32_e32 v82, s2, v2
	v_cmp_ge_i32_e64 s[16:17], s14, v82
	v_lshl_add_u64 v[80:81], v[8:9], 0, s[10:11]
	s_nop 0
	v_cndmask_b32_e64 v80, v8, v80, s[16:17]
	v_cndmask_b32_e64 v81, v9, v81, s[16:17]
	global_load_dwordx4 v[16:19], v[80:81], off
	global_load_dwordx4 v[20:23], v[80:81], off offset:16
	global_load_dwordx4 v[24:27], v[80:81], off offset:32
	global_load_dwordx4 v[28:31], v[80:81], off offset:48
	v_mov_b32_e32 v2, v82
	v_mov_b32_e32 v8, v80
	v_mov_b32_e32 v9, v81
	s_waitcnt vmcnt(4)
	v_pk_mul_f32 v[48:49], v[64:65], v[64:65]
	v_pk_fma_f32 v[48:49], v[66:67], v[66:67], v[48:49]
	v_pk_fma_f32 v[48:49], v[68:69], v[68:69], v[48:49]
	v_pk_fma_f32 v[48:49], v[70:71], v[70:71], v[48:49]
	v_pk_fma_f32 v[48:49], v[72:73], v[72:73], v[48:49]
	v_pk_fma_f32 v[48:49], v[74:75], v[74:75], v[48:49]
	v_pk_fma_f32 v[48:49], v[76:77], v[76:77], v[48:49]
	v_pk_fma_f32 v[48:49], v[78:79], v[78:79], v[48:49]
	v_add_f32_e32 v15, v48, v49
	ds_bpermute_b32 v48, v1, v15
	s_waitcnt lgkmcnt(0)
	v_add_f32_e32 v15, v15, v48
	ds_bpermute_b32 v48, v10, v15
	s_waitcnt lgkmcnt(0)
	v_add_f32_e32 v15, v15, v48
	ds_bpermute_b32 v48, v11, v15
	s_waitcnt lgkmcnt(0)
	v_add_f32_e32 v15, v15, v48
	ds_bpermute_b32 v48, v12, v15
	s_waitcnt lgkmcnt(0)
	v_add_f32_e32 v15, v15, v48
	ds_bpermute_b32 v48, v13, v15
	s_waitcnt lgkmcnt(0)
	v_add_f32_e32 v15, v15, v48
	ds_bpermute_b32 v48, v14, v15
	s_waitcnt lgkmcnt(0)
	v_add_f32_e32 v15, v15, v48
	v_fmamk_f32 v15, v15, 0x3a800000, v3
	v_mul_f32_e32 v48, 0x4b800000, v15
	v_cmp_gt_f32_e32 vcc, s3, v15
	s_nop 1
	v_cndmask_b32_e32 v15, v15, v48, vcc
	v_rsq_f32_e32 v15, v15
	s_nop 0
	v_mul_f32_e32 v48, 0x45800000, v15
	v_cndmask_b32_e32 v48, v15, v48, vcc
	v_pk_mul_f32 v[64:65], v[64:65], v[48:49] op_sel_hi:[1,0]
	v_pk_mul_f32 v[66:67], v[66:67], v[48:49] op_sel_hi:[1,0]
	v_pk_mul_f32 v[68:69], v[68:69], v[48:49] op_sel_hi:[1,0]
	v_pk_mul_f32 v[70:71], v[70:71], v[48:49] op_sel_hi:[1,0]
	v_pk_mul_f32 v[72:73], v[72:73], v[48:49] op_sel_hi:[1,0]
	v_pk_mul_f32 v[74:75], v[74:75], v[48:49] op_sel_hi:[1,0]
	v_pk_mul_f32 v[76:77], v[76:77], v[48:49] op_sel_hi:[1,0]
	v_pk_mul_f32 v[78:79], v[78:79], v[48:49] op_sel_hi:[1,0]
	v_pk_mul_f32 v[64:65], v[64:65], v[36:37]
	v_pk_mul_f32 v[66:67], v[66:67], v[38:39]
	v_pk_mul_f32 v[68:69], v[68:69], v[32:33]
	v_pk_mul_f32 v[70:71], v[70:71], v[34:35]
	v_pk_mul_f32 v[72:73], v[72:73], v[44:45]
	v_pk_mul_f32 v[74:75], v[74:75], v[46:47]
	v_pk_mul_f32 v[76:77], v[76:77], v[40:41]
	v_pk_mul_f32 v[78:79], v[78:79], v[42:43]
	v_cvt_pk_bf16_f32 v64, v64, v65
	v_cvt_pk_bf16_f32 v65, v66, v67
	v_cvt_pk_bf16_f32 v66, v68, v69
	v_cvt_pk_bf16_f32 v67, v70, v71
	v_cvt_pk_bf16_f32 v68, v72, v73
	v_cvt_pk_bf16_f32 v69, v74, v75
	v_cvt_pk_bf16_f32 v70, v76, v77
	v_cvt_pk_bf16_f32 v71, v78, v79
	global_store_dwordx4 v[6:7], v[64:67], off offset:-16
	global_store_dwordx4 v[6:7], v[68:71], off
	v_lshl_add_u64 v[6:7], v[6:7], 0, s[8:9]
	s_and_b64 vcc, exec, s[16:17]
	s_cbranch_vccz .Lp0_done
	s_branch .LBB0_122
.Lp0_done:
.LBB0_123:
	s_or_b64 exec, exec, s[0:1]
